# scan: packed row-pair stepper + counted lgkmcnt + producer prefetch pipeline; diff-attn fast tile path
# speedup vs baseline: 1.0157x; 1.0139x over previous
; __device__ __forceinline__ void scan_job(LAS unsigned char* lds, const AP a, int l, int bl, int hd, int rh) {
;     ...
;     if (producer) SCAN_PROLOGUE(0);
;     __syncthreads();
.LBB0_247:
	s_or_b64 exec, exec, s[24:25]
	s_lshl_b64 s[4:5], s[4:5], 23
	s_add_u32 s4, s15, s4
	s_addc_u32 s5, s14, s5
	s_lshl_b32 s12, s12, 2
	s_add_u32 s4, s4, s12
	s_addc_u32 s5, s5, 0
	s_lshl_b32 s12, s17, 7
	s_add_u32 s4, s4, s12
	s_addc_u32 s5, s5, 0
	s_add_u32 s4, s4, 0x1d900000
	v_lshlrev_b32_e32 v26, 1, v86
	s_addc_u32 s5, s5, 0
	v_lshl_or_b32 v89, s17, 5, v26
	v_mul_u32_u24_e32 v88, 0x880, v87
	v_lshlrev_b32_e32 v26, 3, v48
	v_mov_b32_e32 v27, v1
	v_add3_u32 v90, 0, v88, v26
	v_lshl_add_u64 v[68:69], s[4:5], 0, v[26:27]
	v_lshlrev_b64 v[26:27], 1, v[0:1]
	v_lshl_add_u64 v[70:71], s[6:7], 0, v[26:27]
	s_add_i32 s6, 0, 0x100
	v_lshl_add_u32 v92, v48, 4, s6
	s_add_i32 s6, s12, 0
	v_lshlrev_b32_e32 v0, 3, v86
	s_addk_i32 s6, 0x3100
	v_mul_u32_u24_e32 v28, 0x88, v48
	v_add_u32_e32 v93, s6, v0
	s_add_i32 s6, 0, 0xc000
	v_add3_u32 v94, v28, v0, s6
	v_mov_b32_e32 v0, v1
	v_lshlrev_b32_e32 v66, 1, v48
	v_lshl_add_u64 v[72:73], s[20:21], 0, v[26:27]
	v_lshl_add_u32 v91, v38, 2, 0
	s_mov_b32 s12, 0
	s_mov_b64 s[6:7], 0
	v_mov_b64_e32 v[74:75], v[0:1]
	v_mov_b64_e32 v[76:77], v[0:1]
	v_mov_b64_e32 v[78:79], v[0:1]
	v_mov_b64_e32 v[80:81], v[0:1]
	s_and_saveexec_b64 s[98:99], s[38:39]
	s_cbranch_execz .Lsc_pre_skip
	v_or_b32_e32 v140, 16, v87
	v_mad_u64_u32 v[136:137], vcc, v140, s37, v[72:73]
	v_mad_u64_u32 v[138:139], vcc, v140, s11, v[70:71]
	global_load_dwordx2 v[122:123], v[136:137], off
	global_load_dwordx2 v[126:127], v[138:139], off
	global_load_dwordx2 v[128:129], v[138:139], off offset:-3584
	global_load_dwordx2 v[120:121], v[136:137], off offset:1024
	global_load_dwordx2 v[130:131], v[138:139], off offset:2048
	global_load_dwordx2 v[132:133], v[138:139], off offset:-1536
	global_load_dwordx2 v[134:135], v[138:139], off offset:1024
	global_load_dwordx2 v[124:125], v[138:139], off offset:-2560
.Lsc_pre_skip:
	s_or_b64 exec, exec, s[98:99]
	s_waitcnt lgkmcnt(0)
	s_barrier
	s_branch .LBB0_250

; #define LAS __attribute__((address_space(3)))
; __device__ __forceinline__ void scan_job(LAS unsigned char* lds, const AP a, int l, int bl, int hd, int rh) {
;     ...
;             const LAS float* bp = vec + (ch & 1) * BUFSZ; LAS float* yl = Yp + (ch & 1) * YBUF + jq * YSTR + 2 * srow;
;             const int o0 = jq * 4, vo = 3 * VSZ + rh * 32 + 2 * srow;
;             f32x4 rN = *(const LAS f32x4*)(bp + o0), wN = *(const LAS f32x4*)(bp + VSZ + o0), kN = *(const LAS f32x4*)(bp + 2 * VSZ + o0), kkN = *(const LAS f32x4*)(bp + 4 * VSZ + o0), bN = *(const LAS f32x4*)(bp + 5 * VSZ + o0);
;             f32x2 vN = *(const LAS f32x2*)(bp + vo);
; #pragma unroll 4
;             for (int st = 0; st < CH; ++st) {
;                 const f32x4 w = wN, kk = kkN, b = bN, k = kN, r = rN; const f32x2 v = vN;
;                 const int on = ((st + 1) & (CH - 1)) * 64;
;                 rN = *(const LAS f32x4*)(bp + on + o0); wN = *(const LAS f32x4*)(bp + VSZ + on + o0); kN = *(const LAS f32x4*)(bp + 2 * VSZ + on + o0); kkN = *(const LAS f32x4*)(bp + 4 * VSZ + on + o0); bN = *(const LAS f32x4*)(bp + 5 * VSZ + on + o0);
;                 vN = *(const LAS f32x2*)(bp + on + vo);
;                 const f32x2 kk0 = {kk.x, kk.y}, kk1 = {kk.z, kk.w}, w0 = {w.x, w.y}, w1 = {w.z, w.w}, b0 = {b.x, b.y}, b1 = {b.z, b.w}, k0 = {k.x, k.y}, k1 = {k.z, k.w}, r0 = {r.x, r.y}, r1 = {r.z, r.w};
;                 const f32x2 va = {v.x, v.x}, vb = {v.y, v.y};
;                 const f32x2 pa = sA0 * kk0 + sA1 * kk1, pb = sB0 * kk0 + sB1 * kk1;
;                 const float saA = -red16(pa.x + pa.y), saB = -red16(pb.x + pb.y);
;                 const f32x2 sav = {saA, saA}, sbv = {saB, saB};
;                 sA0 = sA0 * w0 + (sav * b0 + va * k0); sA1 = sA1 * w1 + (sav * b1 + va * k1);
;                 sB0 = sB0 * w0 + (sbv * b0 + vb * k0); sB1 = sB1 * w1 + (sbv * b1 + vb * k1);
;                 const f32x2 ya = sA0 * r0 + sA1 * r1, yb = sB0 * r0 + sB1 * r1;
;                 *(LAS f32x2*)(yl + st * 16 * YSTR) = (f32x2){ya.x + ya.y, yb.x + yb.y};
.LBB0_250:
	s_and_saveexec_b64 s[14:15], s[40:41]
	s_xor_b64 s[20:21], exec, s[14:15]
	s_cbranch_execz .LBB0_254
	v_cndmask_b32_e64 v26, 0, 1, s[6:7]
	s_movk_i32 s14, 0x6000
	v_mul_lo_u32 v27, v26, s14
	s_mov_b32 s14, 0x8800
	v_mul_lo_u32 v26, v26, s14
	v_add_u32_e32 v0, v92, v27
	v_add_u32_e32 v95, v93, v27
	v_add_u32_e32 v96, v94, v26
	s_setprio 3
	s_and_b32 s14, s12, 1
	s_mulk_i32 s14, 0x6000
	s_add_i32 s14, s14, 0
	v_lshl_add_u32 v97, v67, 2, s14
	ds_read_b128 v[26:29], v97
	ds_read_b128 v[30:33], v97 offset:4096
	ds_read_b128 v[34:37], v97 offset:8192
	ds_read_b128 v[42:45], v97 offset:16384
	v_lshl_add_u32 v46, v89, 2, s14
	ds_read_b128 v[38:41], v97 offset:20480
	ds_read_b64 v[82:83], v46 offset:12288
	s_movk_i32 s15, 0x100
	s_waitcnt lgkmcnt(0)
.LBB0_252:
	s_waitcnt lgkmcnt(1)
	ds_read_b128 v[46:49], v0
	ds_read_b128 v[50:53], v0 offset:4096
	ds_read_b128 v[54:57], v0 offset:8192
	ds_read_b128 v[62:65], v0 offset:16384
	ds_read_b128 v[58:61], v0 offset:20480
	ds_read_b64 v[84:85], v95
	v_pk_mul_f32 v[112:113], v[74:75], v[42:43] op_sel_hi:[1,0]
	v_pk_mul_f32 v[104:105], v[82:83], v[34:35] op_sel_hi:[1,0]
	v_pk_fma_f32 v[112:113], v[76:77], v[42:43], v[112:113] op_sel:[0,1,0]
	v_pk_mul_f32 v[106:107], v[82:83], v[34:35] op_sel:[0,1]
	v_pk_fma_f32 v[112:113], v[78:79], v[44:45], v[112:113] op_sel_hi:[1,0,1]
	v_pk_mul_f32 v[108:109], v[82:83], v[36:37] op_sel_hi:[1,0]
	v_pk_fma_f32 v[112:113], v[80:81], v[44:45], v[112:113] op_sel:[0,1,0]
	v_pk_mul_f32 v[110:111], v[82:83], v[36:37] op_sel:[0,1]
	v_pk_fma_f32 v[104:105], v[74:75], v[30:31], v[104:105] op_sel_hi:[1,0,1]
	v_pk_fma_f32 v[106:107], v[76:77], v[30:31], v[106:107] op_sel:[0,1,0]
	v_add_f32_dpp v112, v112, v112 quad_perm:[1,0,3,2] row_mask:0xf bank_mask:0xf bound_ctrl:1
	v_add_f32_dpp v113, v113, v113 quad_perm:[1,0,3,2] row_mask:0xf bank_mask:0xf bound_ctrl:1
	v_pk_fma_f32 v[108:109], v[78:79], v[32:33], v[108:109] op_sel_hi:[1,0,1]
	v_add_f32_dpp v112, v112, v112 quad_perm:[2,3,0,1] row_mask:0xf bank_mask:0xf bound_ctrl:1
	v_add_f32_dpp v113, v113, v113 quad_perm:[2,3,0,1] row_mask:0xf bank_mask:0xf bound_ctrl:1
	v_pk_fma_f32 v[110:111], v[80:81], v[32:33], v[110:111] op_sel:[0,1,0]
	v_add_f32_dpp v112, v112, v112 row_half_mirror row_mask:0xf bank_mask:0xf bound_ctrl:1
	v_add_f32_dpp v113, v113, v113 row_half_mirror row_mask:0xf bank_mask:0xf bound_ctrl:1
	s_nop 0
	v_add_f32_dpp v112, v112, v112 row_mirror row_mask:0xf bank_mask:0xf bound_ctrl:1
	v_add_f32_dpp v113, v113, v113 row_mirror row_mask:0xf bank_mask:0xf bound_ctrl:1
	v_pk_fma_f32 v[74:75], v[112:113], v[38:39], v[104:105] op_sel_hi:[1,0,1] neg_lo:[1,0,0] neg_hi:[1,0,0]
	v_pk_fma_f32 v[76:77], v[112:113], v[38:39], v[106:107] op_sel:[0,1,0] neg_lo:[1,0,0] neg_hi:[1,0,0]
	v_pk_fma_f32 v[78:79], v[112:113], v[40:41], v[108:109] op_sel_hi:[1,0,1] neg_lo:[1,0,0] neg_hi:[1,0,0]
	v_pk_fma_f32 v[80:81], v[112:113], v[40:41], v[110:111] op_sel:[0,1,0] neg_lo:[1,0,0] neg_hi:[1,0,0]
	v_pk_mul_f32 v[114:115], v[74:75], v[26:27] op_sel_hi:[1,0]
	v_pk_fma_f32 v[114:115], v[76:77], v[26:27], v[114:115] op_sel:[0,1,0]
	v_pk_fma_f32 v[114:115], v[78:79], v[28:29], v[114:115] op_sel_hi:[1,0,1]
	v_pk_fma_f32 v[114:115], v[80:81], v[28:29], v[114:115] op_sel:[0,1,0]
	ds_write_b64 v96, v[114:115]
	s_waitcnt lgkmcnt(1)
	ds_read_b128 v[26:29], v0 offset:256
	ds_read_b128 v[30:33], v0 offset:4352
	ds_read_b128 v[34:37], v0 offset:8448
	ds_read_b128 v[42:45], v0 offset:16640
	ds_read_b128 v[38:41], v0 offset:20736
	ds_read_b64 v[82:83], v95 offset:256
	v_pk_mul_f32 v[112:113], v[74:75], v[62:63] op_sel_hi:[1,0]
	v_pk_mul_f32 v[104:105], v[84:85], v[54:55] op_sel_hi:[1,0]
	v_pk_fma_f32 v[112:113], v[76:77], v[62:63], v[112:113] op_sel:[0,1,0]
	v_pk_mul_f32 v[106:107], v[84:85], v[54:55] op_sel:[0,1]
	v_pk_fma_f32 v[112:113], v[78:79], v[64:65], v[112:113] op_sel_hi:[1,0,1]
	v_pk_mul_f32 v[108:109], v[84:85], v[56:57] op_sel_hi:[1,0]
	v_pk_fma_f32 v[112:113], v[80:81], v[64:65], v[112:113] op_sel:[0,1,0]
	v_pk_mul_f32 v[110:111], v[84:85], v[56:57] op_sel:[0,1]
	v_pk_fma_f32 v[104:105], v[74:75], v[50:51], v[104:105] op_sel_hi:[1,0,1]
	v_pk_fma_f32 v[106:107], v[76:77], v[50:51], v[106:107] op_sel:[0,1,0]
	v_add_f32_dpp v112, v112, v112 quad_perm:[1,0,3,2] row_mask:0xf bank_mask:0xf bound_ctrl:1
	v_add_f32_dpp v113, v113, v113 quad_perm:[1,0,3,2] row_mask:0xf bank_mask:0xf bound_ctrl:1
	v_pk_fma_f32 v[108:109], v[78:79], v[52:53], v[108:109] op_sel_hi:[1,0,1]
	v_add_f32_dpp v112, v112, v112 quad_perm:[2,3,0,1] row_mask:0xf bank_mask:0xf bound_ctrl:1
	v_add_f32_dpp v113, v113, v113 quad_perm:[2,3,0,1] row_mask:0xf bank_mask:0xf bound_ctrl:1
	v_pk_fma_f32 v[110:111], v[80:81], v[52:53], v[110:111] op_sel:[0,1,0]
	v_add_f32_dpp v112, v112, v112 row_half_mirror row_mask:0xf bank_mask:0xf bound_ctrl:1
	v_add_f32_dpp v113, v113, v113 row_half_mirror row_mask:0xf bank_mask:0xf bound_ctrl:1
	s_nop 0
	v_add_f32_dpp v112, v112, v112 row_mirror row_mask:0xf bank_mask:0xf bound_ctrl:1
	v_add_f32_dpp v113, v113, v113 row_mirror row_mask:0xf bank_mask:0xf bound_ctrl:1
	v_pk_fma_f32 v[74:75], v[112:113], v[58:59], v[104:105] op_sel_hi:[1,0,1] neg_lo:[1,0,0] neg_hi:[1,0,0]
	v_pk_fma_f32 v[76:77], v[112:113], v[58:59], v[106:107] op_sel:[0,1,0] neg_lo:[1,0,0] neg_hi:[1,0,0]
	v_pk_fma_f32 v[78:79], v[112:113], v[60:61], v[108:109] op_sel_hi:[1,0,1] neg_lo:[1,0,0] neg_hi:[1,0,0]
	v_pk_fma_f32 v[80:81], v[112:113], v[60:61], v[110:111] op_sel:[0,1,0] neg_lo:[1,0,0] neg_hi:[1,0,0]
	v_pk_mul_f32 v[114:115], v[74:75], v[46:47] op_sel_hi:[1,0]
	v_pk_fma_f32 v[114:115], v[76:77], v[46:47], v[114:115] op_sel:[0,1,0]
	v_pk_fma_f32 v[114:115], v[78:79], v[48:49], v[114:115] op_sel_hi:[1,0,1]
	v_pk_fma_f32 v[114:115], v[80:81], v[48:49], v[114:115] op_sel:[0,1,0]
	ds_write_b64 v96, v[114:115] offset:2176
	s_waitcnt lgkmcnt(1)
; #define LAS __attribute__((address_space(3)))
; #define SCAN_FLUSH(chn) do { const LAS float* yp = Yp + ((chn) & 1) * YBUF + tt * 16 * YSTR + 2 * jq; f32x2 acc_ = {0.f, 0.f}; \
;           _Pragma("unroll") for (int q_ = 0; q_ < 16; ++q_) { const f32x2 x_ = *(const LAS f32x2*)(yp + q_ * YSTR); acc_.x += x_.x; acc_.y += x_.y; } \
;           stg<f32x2>(Yg + (size_t)((chn) * CH + tt) * 512 + 2 * jq, acc_); } while (0)
; __device__ __forceinline__ void scan_job(LAS unsigned char* lds, const AP a, int l, int bl, int hd, int rh) {
;     ...
;         if (producer) {
;             if (ch > 0) SCAN_FLUSH(ch - 1);
;             if (ch + 1 < NCH) SCAN_PROLOGUE(ch + 1);
;     ...
;             for (int st = 0; st < CH; ++st) {
;                 const f32x4 w = wN, kk = kkN, b = bN, k = kN, r = rN; const f32x2 v = vN;
;                 const int on = ((st + 1) & (CH - 1)) * 64;
;                 rN = *(const LAS f32x4*)(bp + on + o0); wN = *(const LAS f32x4*)(bp + VSZ + on + o0); kN = *(const LAS f32x4*)(bp + 2 * VSZ + on + o0); kkN = *(const LAS f32x4*)(bp + 4 * VSZ + on + o0); bN = *(const LAS f32x4*)(bp + 5 * VSZ + on + o0);
;                 vN = *(const LAS f32x2*)(bp + on + vo);
;                 const f32x2 kk0 = {kk.x, kk.y}, kk1 = {kk.z, kk.w}, w0 = {w.x, w.y}, w1 = {w.z, w.w}, b0 = {b.x, b.y}, b1 = {b.z, b.w}, k0 = {k.x, k.y}, k1 = {k.z, k.w}, r0 = {r.x, r.y}, r1 = {r.z, r.w};
;                 const f32x2 va = {v.x, v.x}, vb = {v.y, v.y};
;                 const f32x2 pa = sA0 * kk0 + sA1 * kk1, pb = sB0 * kk0 + sB1 * kk1;
;                 const float saA = -red16(pa.x + pa.y), saB = -red16(pb.x + pb.y);
;                 const f32x2 sav = {saA, saA}, sbv = {saB, saB};
;                 sA0 = sA0 * w0 + (sav * b0 + va * k0); sA1 = sA1 * w1 + (sav * b1 + va * k1);
;                 sB0 = sB0 * w0 + (sbv * b0 + vb * k0); sB1 = sB1 * w1 + (sbv * b1 + vb * k1);
;                 const f32x2 ya = sA0 * r0 + sA1 * r1, yb = sB0 * r0 + sB1 * r1;
;                 *(LAS f32x2*)(yl + st * 16 * YSTR) = (f32x2){ya.x + ya.y, yb.x + yb.y};
;             }
	ds_read_b128 v[46:49], v0 offset:512
	ds_read_b128 v[50:53], v0 offset:4608
	ds_read_b128 v[54:57], v0 offset:8704
	ds_read_b128 v[62:65], v0 offset:16896
	ds_read_b128 v[58:61], v0 offset:20992
	ds_read_b64 v[84:85], v95 offset:512
	v_pk_mul_f32 v[112:113], v[74:75], v[42:43] op_sel_hi:[1,0]
	v_pk_mul_f32 v[104:105], v[82:83], v[34:35] op_sel_hi:[1,0]
	v_pk_fma_f32 v[112:113], v[76:77], v[42:43], v[112:113] op_sel:[0,1,0]
	v_pk_mul_f32 v[106:107], v[82:83], v[34:35] op_sel:[0,1]
	v_pk_fma_f32 v[112:113], v[78:79], v[44:45], v[112:113] op_sel_hi:[1,0,1]
	v_pk_mul_f32 v[108:109], v[82:83], v[36:37] op_sel_hi:[1,0]
	v_pk_fma_f32 v[112:113], v[80:81], v[44:45], v[112:113] op_sel:[0,1,0]
	v_pk_mul_f32 v[110:111], v[82:83], v[36:37] op_sel:[0,1]
	v_pk_fma_f32 v[104:105], v[74:75], v[30:31], v[104:105] op_sel_hi:[1,0,1]
	v_pk_fma_f32 v[106:107], v[76:77], v[30:31], v[106:107] op_sel:[0,1,0]
	v_add_f32_dpp v112, v112, v112 quad_perm:[1,0,3,2] row_mask:0xf bank_mask:0xf bound_ctrl:1
	v_add_f32_dpp v113, v113, v113 quad_perm:[1,0,3,2] row_mask:0xf bank_mask:0xf bound_ctrl:1
	v_pk_fma_f32 v[108:109], v[78:79], v[32:33], v[108:109] op_sel_hi:[1,0,1]
	v_add_f32_dpp v112, v112, v112 quad_perm:[2,3,0,1] row_mask:0xf bank_mask:0xf bound_ctrl:1
	v_add_f32_dpp v113, v113, v113 quad_perm:[2,3,0,1] row_mask:0xf bank_mask:0xf bound_ctrl:1
	v_pk_fma_f32 v[110:111], v[80:81], v[32:33], v[110:111] op_sel:[0,1,0]
	v_add_f32_dpp v112, v112, v112 row_half_mirror row_mask:0xf bank_mask:0xf bound_ctrl:1
	v_add_f32_dpp v113, v113, v113 row_half_mirror row_mask:0xf bank_mask:0xf bound_ctrl:1
	s_nop 0
	v_add_f32_dpp v112, v112, v112 row_mirror row_mask:0xf bank_mask:0xf bound_ctrl:1
	v_add_f32_dpp v113, v113, v113 row_mirror row_mask:0xf bank_mask:0xf bound_ctrl:1
	v_pk_fma_f32 v[74:75], v[112:113], v[38:39], v[104:105] op_sel_hi:[1,0,1] neg_lo:[1,0,0] neg_hi:[1,0,0]
	v_pk_fma_f32 v[76:77], v[112:113], v[38:39], v[106:107] op_sel:[0,1,0] neg_lo:[1,0,0] neg_hi:[1,0,0]
	v_pk_fma_f32 v[78:79], v[112:113], v[40:41], v[108:109] op_sel_hi:[1,0,1] neg_lo:[1,0,0] neg_hi:[1,0,0]
	v_pk_fma_f32 v[80:81], v[112:113], v[40:41], v[110:111] op_sel:[0,1,0] neg_lo:[1,0,0] neg_hi:[1,0,0]
	v_pk_mul_f32 v[114:115], v[74:75], v[26:27] op_sel_hi:[1,0]
	v_pk_fma_f32 v[114:115], v[76:77], v[26:27], v[114:115] op_sel:[0,1,0]
	v_pk_fma_f32 v[114:115], v[78:79], v[28:29], v[114:115] op_sel_hi:[1,0,1]
	v_pk_fma_f32 v[114:115], v[80:81], v[28:29], v[114:115] op_sel:[0,1,0]
	ds_write_b64 v96, v[114:115] offset:4352
	s_waitcnt lgkmcnt(1)
	ds_read_b128 v[26:29], v0 offset:768
	ds_read_b128 v[30:33], v0 offset:4864
	ds_read_b128 v[34:37], v0 offset:8960
	ds_read_b128 v[42:45], v0 offset:17152
	ds_read_b128 v[38:41], v0 offset:21248
	ds_read_b64 v[82:83], v95 offset:768
	v_pk_mul_f32 v[112:113], v[74:75], v[62:63] op_sel_hi:[1,0]
	v_pk_mul_f32 v[104:105], v[84:85], v[54:55] op_sel_hi:[1,0]
	v_pk_fma_f32 v[112:113], v[76:77], v[62:63], v[112:113] op_sel:[0,1,0]
	v_pk_mul_f32 v[106:107], v[84:85], v[54:55] op_sel:[0,1]
	v_pk_fma_f32 v[112:113], v[78:79], v[64:65], v[112:113] op_sel_hi:[1,0,1]
	v_pk_mul_f32 v[108:109], v[84:85], v[56:57] op_sel_hi:[1,0]
	v_pk_fma_f32 v[112:113], v[80:81], v[64:65], v[112:113] op_sel:[0,1,0]
	v_pk_mul_f32 v[110:111], v[84:85], v[56:57] op_sel:[0,1]
	v_pk_fma_f32 v[104:105], v[74:75], v[50:51], v[104:105] op_sel_hi:[1,0,1]
	v_pk_fma_f32 v[106:107], v[76:77], v[50:51], v[106:107] op_sel:[0,1,0]
	v_add_f32_dpp v112, v112, v112 quad_perm:[1,0,3,2] row_mask:0xf bank_mask:0xf bound_ctrl:1
	v_add_f32_dpp v113, v113, v113 quad_perm:[1,0,3,2] row_mask:0xf bank_mask:0xf bound_ctrl:1
	v_pk_fma_f32 v[108:109], v[78:79], v[52:53], v[108:109] op_sel_hi:[1,0,1]
	v_add_f32_dpp v112, v112, v112 quad_perm:[2,3,0,1] row_mask:0xf bank_mask:0xf bound_ctrl:1
	v_add_f32_dpp v113, v113, v113 quad_perm:[2,3,0,1] row_mask:0xf bank_mask:0xf bound_ctrl:1
	v_pk_fma_f32 v[110:111], v[80:81], v[52:53], v[110:111] op_sel:[0,1,0]
	v_add_f32_dpp v112, v112, v112 row_half_mirror row_mask:0xf bank_mask:0xf bound_ctrl:1
	v_add_f32_dpp v113, v113, v113 row_half_mirror row_mask:0xf bank_mask:0xf bound_ctrl:1
	s_nop 0
	v_add_f32_dpp v112, v112, v112 row_mirror row_mask:0xf bank_mask:0xf bound_ctrl:1
	v_add_f32_dpp v113, v113, v113 row_mirror row_mask:0xf bank_mask:0xf bound_ctrl:1
	v_pk_fma_f32 v[74:75], v[112:113], v[58:59], v[104:105] op_sel_hi:[1,0,1] neg_lo:[1,0,0] neg_hi:[1,0,0]
	v_pk_fma_f32 v[76:77], v[112:113], v[58:59], v[106:107] op_sel:[0,1,0] neg_lo:[1,0,0] neg_hi:[1,0,0]
	v_pk_fma_f32 v[78:79], v[112:113], v[60:61], v[108:109] op_sel_hi:[1,0,1] neg_lo:[1,0,0] neg_hi:[1,0,0]
	v_pk_fma_f32 v[80:81], v[112:113], v[60:61], v[110:111] op_sel:[0,1,0] neg_lo:[1,0,0] neg_hi:[1,0,0]
	v_pk_mul_f32 v[114:115], v[74:75], v[46:47] op_sel_hi:[1,0]
	v_pk_fma_f32 v[114:115], v[76:77], v[46:47], v[114:115] op_sel:[0,1,0]
	v_pk_fma_f32 v[114:115], v[78:79], v[48:49], v[114:115] op_sel_hi:[1,0,1]
	v_pk_fma_f32 v[114:115], v[80:81], v[48:49], v[114:115] op_sel:[0,1,0]
	ds_write_b64 v96, v[114:115] offset:6528
	s_addk_i32 s15, 0x100
	v_add_u32_e32 v0, 0x400, v0
	s_cmpk_eq_i32 s15, 0x500
	v_add_u32_e32 v95, 0x400, v95
	v_add_u32_e32 v96, 0x2200, v96
	s_cbranch_scc0 .LBB0_252
	s_setprio 0
.LBB0_254:
	s_andn2_saveexec_b64 s[20:21], s[20:21]
	s_cbranch_execz .LBB0_249
	s_cmpk_eq_i32 s12, 0xff
	s_cbranch_scc1 .Lsc_flush
	s_cmp_lt_u32 s12, 2
	s_cbranch_scc1 .Lsc_w0
	s_waitcnt vmcnt(1)
	s_branch .Lsc_w1

.Lsc_w1:
	v_mov_b64_e32 v[26:27], v[120:121]
	v_mov_b64_e32 v[28:29], v[122:123]
	v_mov_b64_e32 v[30:31], v[124:125]
	v_mov_b64_e32 v[32:33], v[126:127]
	v_mov_b64_e32 v[34:35], v[128:129]
	v_mov_b64_e32 v[36:37], v[130:131]
	v_mov_b64_e32 v[38:39], v[132:133]
	v_mov_b64_e32 v[40:41], v[134:135]
	s_cmpk_ge_i32 s12, 0xfe
	s_cbranch_scc1 .Lsc_nopf
	s_add_i32 s17, s12, 2
	v_lshl_or_b32 v140, s17, 4, v87
	v_mad_u64_u32 v[136:137], vcc, v140, s37, v[72:73]
	v_mad_u64_u32 v[138:139], vcc, v140, s11, v[70:71]
	global_load_dwordx2 v[122:123], v[136:137], off
	global_load_dwordx2 v[126:127], v[138:139], off
	global_load_dwordx2 v[128:129], v[138:139], off offset:-3584
	global_load_dwordx2 v[120:121], v[136:137], off offset:1024
	global_load_dwordx2 v[130:131], v[138:139], off offset:2048
	global_load_dwordx2 v[132:133], v[138:139], off offset:-1536
	global_load_dwordx2 v[134:135], v[138:139], off offset:1024
	global_load_dwordx2 v[124:125], v[138:139], off offset:-2560
.Lsc_nopf:
	s_add_i32 s17, s12, 1
	v_lshl_or_b32 v0, s17, 4, v87
	s_waitcnt lgkmcnt(0)
	s_bitcmp1_b32 s17, 0
	s_cselect_b32 s14, 0x6000, 0
	v_lshlrev_b32_e32 v48, 16, v33
	v_lshlrev_b32_e32 v42, 16, v34
	v_and_b32_e32 v43, 0xffff0000, v34
	v_lshlrev_b32_e32 v44, 16, v36
	v_and_b32_e32 v45, 0xffff0000, v36
	v_lshlrev_b32_e32 v56, 16, v28
	v_and_b32_e32 v57, 0xffff0000, v28
	v_lshlrev_b32_e32 v58, 16, v29
	v_and_b32_e32 v59, 0xffff0000, v29
	v_lshlrev_b32_e32 v28, 16, v32
	v_and_b32_e32 v29, 0xffff0000, v32
	v_lshlrev_b32_e32 v46, 16, v38
	v_and_b32_e32 v47, 0xffff0000, v38
	v_and_b32_e32 v49, 0xffff0000, v33
	v_lshlrev_b32_e32 v32, 16, v35
	v_and_b32_e32 v33, 0xffff0000, v35
	v_lshlrev_b32_e32 v34, 16, v37
	v_and_b32_e32 v35, 0xffff0000, v37
	v_lshlrev_b32_e32 v36, 16, v39
	v_and_b32_e32 v37, 0xffff0000, v39
	v_lshlrev_b32_e32 v38, 16, v40
	v_and_b32_e32 v39, 0xffff0000, v40
	v_lshlrev_b32_e32 v50, 16, v30
	v_and_b32_e32 v51, 0xffff0000, v30
	v_lshlrev_b32_e32 v52, 16, v26
	v_and_b32_e32 v53, 0xffff0000, v26
	v_lshlrev_b32_e32 v40, 16, v41
	v_and_b32_e32 v41, 0xffff0000, v41
	v_lshlrev_b32_e32 v30, 16, v31
	v_and_b32_e32 v31, 0xffff0000, v31
	v_lshlrev_b32_e32 v54, 16, v27
	v_and_b32_e32 v55, 0xffff0000, v27
	v_pk_add_f32 v[26:27], v[42:43], v[28:29] neg_lo:[0,1] neg_hi:[0,1]
	v_pk_add_f32 v[42:43], v[46:47], v[44:45] neg_lo:[0,1] neg_hi:[0,1]
	v_mul_f32_e32 v62, 0xbfb8aa3b, v56
	v_mul_f32_e32 v63, 0xbfb8aa3b, v57
	v_pk_add_f32 v[50:51], v[50:51], v[38:39] neg_lo:[0,1] neg_hi:[0,1]
	v_pk_add_f32 v[56:57], v[52:53], -1.0 op_sel_hi:[1,0]
	v_pk_add_f32 v[46:47], v[32:33], v[48:49] neg_lo:[0,1] neg_hi:[0,1]
	v_mul_f32_e32 v64, 0xbfb8aa3b, v58
	v_mul_f32_e32 v65, 0xbfb8aa3b, v59
	v_pk_add_f32 v[58:59], v[30:31], v[40:41] neg_lo:[0,1] neg_hi:[0,1]
	v_pk_add_f32 v[60:61], v[54:55], -1.0 op_sel_hi:[1,0]
	v_pk_fma_f32 v[28:29], v[10:11], v[26:27], v[28:29]
	v_pk_fma_f32 v[32:33], v[2:3], v[42:43], v[44:45]
	v_pk_fma_f32 v[26:27], v[6:7], v[50:51], v[38:39]
	v_pk_fma_f32 v[42:43], v[18:19], v[56:57], 1.0 op_sel_hi:[1,1,0]
	v_pk_fma_f32 v[30:31], v[12:13], v[46:47], v[48:49]
	v_pk_fma_f32 v[44:45], v[8:9], v[58:59], v[40:41]
	v_pk_fma_f32 v[46:47], v[20:21], v[60:61], 1.0 op_sel_hi:[1,1,0]
	v_pk_mul_f32 v[48:49], v[14:15], v[26:27]
	v_pk_mul_f32 v[40:41], v[26:27], v[42:43]
	v_pk_mul_f32 v[50:51], v[16:17], v[44:45]
	v_pk_mul_f32 v[42:43], v[44:45], v[46:47]
	v_pk_mul_f32 v[26:27], v[48:49], v[48:49]
	v_pk_mul_f32 v[44:45], v[28:29], v[40:41]
	v_pk_mul_f32 v[46:47], v[50:51], v[50:51]
	v_pk_mul_f32 v[44:45], v[22:23], v[44:45]
	v_add_f32_e32 v58, v26, v27
	v_add_f32_e32 v44, 0, v44
	v_add_f32_e32 v46, v46, v58
	v_pk_mul_f32 v[56:57], v[30:31], v[42:43]
	v_add_f32_e32 v44, v45, v44
	v_add_f32_e32 v45, v47, v46
	v_pk_mul_f32 v[26:27], v[24:25], v[56:57]
	v_pk_add_f32 v[36:37], v[36:37], v[34:35] neg_lo:[0,1] neg_hi:[0,1]
	v_add_f32_dpp v45, v45, v45 quad_perm:[1,0,3,2] row_mask:0xf bank_mask:0xf bound_ctrl:1
	v_add_f32_e32 v26, v26, v44
	v_add_f32_e32 v26, v27, v26
	v_add_f32_dpp v44, v45, v45 quad_perm:[2,3,0,1] row_mask:0xf bank_mask:0xf bound_ctrl:1
	v_pk_fma_f32 v[34:35], v[4:5], v[36:37], v[34:35]
	v_add_f32_dpp v26, v26, v26 quad_perm:[1,0,3,2] row_mask:0xf bank_mask:0xf bound_ctrl:1
	v_add_f32_dpp v27, v44, v44 row_half_mirror row_mask:0xf bank_mask:0xf bound_ctrl:1
	v_exp_f32_e32 v36, v62
	v_exp_f32_e32 v37, v63
	v_add_f32_dpp v27, v27, v27 row_mirror row_mask:0xf bank_mask:0xf bound_ctrl:1
	v_rsq_f32_e32 v27, v27
	v_exp_f32_e32 v38, v64
	v_exp_f32_e32 v39, v65
	v_add_f32_dpp v26, v26, v26 quad_perm:[2,3,0,1] row_mask:0xf bank_mask:0xf bound_ctrl:1
	v_min_f32_e32 v46, 0x5368d4a5, v27
	v_pk_mul_f32 v[44:45], v[48:49], v[46:47] op_sel_hi:[1,0]
	v_add_f32_dpp v26, v26, v26 row_half_mirror row_mask:0xf bank_mask:0xf bound_ctrl:1
	v_pk_mul_f32 v[46:47], v[50:51], v[46:47] op_sel_hi:[1,0]
	v_pk_mul_f32 v[48:49], v[44:45], v[52:53]
	v_mov_b32_dpp v27, v26 row_mirror row_mask:0xf bank_mask:0xf bound_ctrl:1
	v_add_u32_e32 v52, s14, v91
	v_pk_mul_f32 v[50:51], v[46:47], v[54:55]
	ds_write_b128 v52, v[28:31]
	ds_write_b128 v52, v[36:39] offset:4096
	ds_write_b128 v52, v[40:43] offset:8192
	ds_write_b128 v52, v[32:35] offset:12288
	ds_write_b128 v52, v[44:47] offset:16384
	ds_write_b128 v52, v[48:51] offset:20480
	s_and_saveexec_b64 s[24:25], s[2:3]
	s_cbranch_execz .Lsc_norkb
	v_lshlrev_b64 v[28:29], 5, v[0:1]
	v_lshl_add_u64 v[28:29], s[0:1], 0, v[28:29]
	v_add_f32_e32 v0, v26, v27
	global_store_dword v[28:29], v0, off

; #define SCAN_FLUSH(chn) do { const LAS float* yp = Yp + ((chn) & 1) * YBUF + tt * 16 * YSTR + 2 * jq; f32x2 acc_ = {0.f, 0.f}; \
;           _Pragma("unroll") for (int q_ = 0; q_ < 16; ++q_) { const f32x2 x_ = *(const LAS f32x2*)(yp + q_ * YSTR); acc_.x += x_.x; acc_.y += x_.y; } \
;           stg<f32x2>(Yg + (size_t)((chn) * CH + tt) * 512 + 2 * jq, acc_); } while (0)
; __device__ __forceinline__ void scan_job(LAS unsigned char* lds, const AP a, int l, int bl, int hd, int rh) {
;     ...
;             if (ch > 0) SCAN_FLUSH(ch - 1);
.Lsc_flush:
	s_cmp_eq_u32 s12, 0
	s_cbranch_scc1 .LBB0_249
	s_add_i32 s14, s12, -1
	s_bitcmp1_b32 s14, 0
	s_cselect_b32 s15, 0x8800, 0
	v_add_u32_e32 v0, s15, v90
	v_add_u32_e32 v0, 0xc000, v0
	s_waitcnt lgkmcnt(0)
	ds_read2_b64 v[26:29], v0 offset1:17
	ds_read2_b64 v[30:33], v0 offset0:34 offset1:51
	ds_read2_b64 v[34:37], v0 offset0:68 offset1:85
	ds_read2_b64 v[38:41], v0 offset0:102 offset1:119
	ds_read2_b64 v[42:45], v0 offset0:136 offset1:153
	s_waitcnt lgkmcnt(0)
	v_pk_add_f32 v[26:27], v[26:27], 0 op_sel_hi:[1,0]
	s_cmpk_lg_i32 s12, 0xff
	v_pk_add_f32 v[26:27], v[26:27], v[28:29]
	s_cselect_b64 s[24:25], -1, 0
	v_pk_add_f32 v[26:27], v[26:27], v[30:31]
	s_nop 0
	v_pk_add_f32 v[26:27], v[26:27], v[32:33]
	s_nop 0
	v_pk_add_f32 v[34:35], v[26:27], v[34:35]
	ds_read2_b64 v[26:29], v0 offset0:170 offset1:187
	ds_read2_b64 v[30:33], v0 offset0:204 offset1:221
	ds_read2_b64 v[46:49], v0 offset0:238 offset1:255
	v_pk_add_f32 v[34:35], v[34:35], v[36:37]
	v_lshl_or_b32 v0, s14, 4, v87
	v_pk_add_f32 v[34:35], v[34:35], v[38:39]
	s_nop 0
	v_pk_add_f32 v[34:35], v[34:35], v[40:41]
	s_nop 0
	v_pk_add_f32 v[34:35], v[34:35], v[42:43]
	s_nop 0
	v_pk_add_f32 v[34:35], v[34:35], v[44:45]
	s_waitcnt lgkmcnt(0)
	v_pk_add_f32 v[26:27], v[34:35], v[26:27]
	s_nop 0
	v_pk_add_f32 v[26:27], v[26:27], v[28:29]
	v_lshlrev_b64 v[28:29], 11, v[0:1]
	v_pk_add_f32 v[26:27], v[26:27], v[30:31]
	v_lshl_add_u64 v[28:29], v[68:69], 0, v[28:29]
	v_pk_add_f32 v[26:27], v[26:27], v[32:33]
	s_nop 0
	v_pk_add_f32 v[26:27], v[26:27], v[46:47]
	s_nop 0
	v_pk_add_f32 v[26:27], v[26:27], v[48:49]
	global_store_dwordx2 v[28:29], v[26:27], off
	s_branch .LBB0_249
